# kpair + drop redundant lgkmcnt(0) after barrier and setprio 0/1 pair between the two MFMA blocks
# speedup vs baseline: 1.0043x; 1.0043x over previous
.LBB0_120:
	s_add_u32 s28, s40, 0xfff80080
	s_addc_u32 s29, s41, -1
	s_add_i32 s54, 0, 0x10000
	s_cmp_eq_u32 s53, 28
	s_cselect_b32 s29, s23, s29
	s_cselect_b32 s28, s22, s28
	s_cselect_b32 s43, s21, s52
	s_cselect_b32 s42, s50, s51
	s_add_i32 s56, 0, 0x14000
	v_add_u32_e32 v142, s54, v212
	v_add_u32_e32 v158, s56, v212
	ds_read_b128 v[130:133], v142
	ds_read_b128 v[134:137], v142 offset:1024
	ds_read_b128 v[138:141], v142 offset:2048
	ds_read_b128 v[142:145], v142 offset:3072
	ds_read_b128 v[146:149], v158
	ds_read_b128 v[150:153], v158 offset:1024
	ds_read_b128 v[154:157], v158 offset:2048
	ds_read_b128 v[158:161], v158 offset:3072
	v_lshl_add_u64 v[204:205], s[40:41], 0, v[184:185]
	s_add_i32 m0, s24, 0xc000
	ds_read_b128 v[162:165], v213
	ds_read_b128 v[166:169], v213 offset:1024
	ds_read_b128 v[170:173], v213 offset:2048
	ds_read_b128 v[174:177], v213 offset:3072
	ds_read_b128 v[188:191], v213 offset:4096
	ds_read_b128 v[192:195], v213 offset:5120
	ds_read_b128 v[196:199], v213 offset:6144
	ds_read_b128 v[200:203], v213 offset:7168
	global_load_lds_dwordx4 v[204:205], off
	v_lshl_add_u64 v[204:205], s[40:41], 0, v[186:187]
	s_add_i32 m0, s24, 0xe000
	s_nop 0
	global_load_lds_dwordx4 v[204:205], off
	s_waitcnt vmcnt(8)
	s_waitcnt lgkmcnt(0)
	s_barrier
	s_setprio 1
	v_mfma_f32_16x16x32_bf16 v[126:129], v[130:133], v[162:165], v[126:129]
	v_mfma_f32_16x16x32_bf16 v[126:129], v[134:137], v[166:169], v[126:129]
	v_mfma_f32_16x16x32_bf16 v[122:125], v[142:145], v[166:169], v[122:125]
	v_mfma_f32_16x16x32_bf16 v[122:125], v[138:141], v[162:165], v[122:125]
	v_mfma_f32_16x16x32_bf16 v[106:109], v[138:141], v[170:173], v[106:109]
	v_mfma_f32_16x16x32_bf16 v[106:109], v[142:145], v[174:177], v[106:109]
	v_mfma_f32_16x16x32_bf16 v[110:113], v[134:137], v[174:177], v[110:113]
	v_mfma_f32_16x16x32_bf16 v[110:113], v[130:133], v[170:173], v[110:113]
	v_mfma_f32_16x16x32_bf16 v[94:97], v[130:133], v[188:191], v[94:97]
	v_mfma_f32_16x16x32_bf16 v[94:97], v[134:137], v[192:195], v[94:97]
	v_mfma_f32_16x16x32_bf16 v[90:93], v[142:145], v[192:195], v[90:93]
	v_mfma_f32_16x16x32_bf16 v[90:93], v[138:141], v[188:191], v[90:93]
	v_mfma_f32_16x16x32_bf16 v[74:77], v[138:141], v[196:199], v[74:77]
	v_mfma_f32_16x16x32_bf16 v[74:77], v[142:145], v[200:203], v[74:77]
	v_mfma_f32_16x16x32_bf16 v[78:81], v[134:137], v[200:203], v[78:81]
	v_mfma_f32_16x16x32_bf16 v[78:81], v[130:133], v[196:199], v[78:81]
	v_mfma_f32_16x16x32_bf16 v[118:121], v[146:149], v[162:165], v[118:121]
	v_mfma_f32_16x16x32_bf16 v[118:121], v[150:153], v[166:169], v[118:121]
	v_mfma_f32_16x16x32_bf16 v[114:117], v[158:161], v[166:169], v[114:117]
	v_mfma_f32_16x16x32_bf16 v[114:117], v[154:157], v[162:165], v[114:117]
	v_mfma_f32_16x16x32_bf16 v[98:101], v[154:157], v[170:173], v[98:101]
	v_mfma_f32_16x16x32_bf16 v[98:101], v[158:161], v[174:177], v[98:101]
	v_mfma_f32_16x16x32_bf16 v[102:105], v[150:153], v[174:177], v[102:105]
	v_mfma_f32_16x16x32_bf16 v[102:105], v[146:149], v[170:173], v[102:105]
	v_mfma_f32_16x16x32_bf16 v[86:89], v[146:149], v[188:191], v[86:89]
	v_mfma_f32_16x16x32_bf16 v[86:89], v[150:153], v[192:195], v[86:89]
	v_mfma_f32_16x16x32_bf16 v[82:85], v[158:161], v[192:195], v[82:85]
	v_mfma_f32_16x16x32_bf16 v[82:85], v[154:157], v[188:191], v[82:85]
	v_mfma_f32_16x16x32_bf16 v[66:69], v[154:157], v[196:199], v[66:69]
	v_mfma_f32_16x16x32_bf16 v[66:69], v[158:161], v[200:203], v[66:69]
	v_mfma_f32_16x16x32_bf16 v[70:73], v[150:153], v[200:203], v[70:73]
	v_mfma_f32_16x16x32_bf16 v[70:73], v[146:149], v[196:199], v[70:73]
	s_setprio 0
	s_barrier
	s_add_i32 s54, s54, s1
	v_lshl_add_u64 v[204:205], s[42:43], 0, v[32:33]
	s_mov_b32 m0, s54
	ds_read_b128 v[162:165], v213 offset:16384
	ds_read_b128 v[166:169], v213 offset:17408
	ds_read_b128 v[170:173], v213 offset:18432
	ds_read_b128 v[174:177], v213 offset:19456
	ds_read_b128 v[188:191], v213 offset:20480
	ds_read_b128 v[192:195], v213 offset:21504
	ds_read_b128 v[196:199], v213 offset:22528
	ds_read_b128 v[200:203], v213 offset:23552
	global_load_lds_dwordx4 v[204:205], off
	s_add_i32 m0, s54, 0x2000
	s_add_u32 s54, s42, 0x80000
	v_lshl_add_u64 v[206:207], s[42:43], 0, v[182:183]
	s_addc_u32 s55, s43, 0
	s_add_i32 s56, s56, s1
	global_load_lds_dwordx4 v[206:207], off
	v_lshl_add_u64 v[208:209], s[54:55], 0, v[32:33]
	s_mov_b32 m0, s56
	v_lshl_add_u64 v[214:215], s[28:29], 0, v[180:181]
	global_load_lds_dwordx4 v[208:209], off
	v_lshl_add_u64 v[208:209], s[54:55], 0, v[182:183]
	s_add_i32 m0, s56, 0x2000
	s_nop 0
	global_load_lds_dwordx4 v[208:209], off
	v_lshl_add_u64 v[208:209], s[28:29], 0, v[178:179]
	s_mov_b32 m0, s24
	s_nop 0
	global_load_lds_dwordx4 v[208:209], off
	s_mov_b32 m0, s25
	s_nop 0
	global_load_lds_dwordx4 v[214:215], off
	s_waitcnt vmcnt(8)
	s_waitcnt lgkmcnt(0)
	s_barrier
	s_setprio 1
	v_mfma_f32_16x16x32_bf16 v[62:65], v[130:133], v[162:165], v[62:65]
	v_mfma_f32_16x16x32_bf16 v[62:65], v[134:137], v[166:169], v[62:65]
	v_mfma_f32_16x16x32_bf16 v[58:61], v[142:145], v[166:169], v[58:61]
	v_mfma_f32_16x16x32_bf16 v[58:61], v[138:141], v[162:165], v[58:61]
	v_mfma_f32_16x16x32_bf16 v[42:45], v[138:141], v[170:173], v[42:45]
	v_mfma_f32_16x16x32_bf16 v[42:45], v[142:145], v[174:177], v[42:45]
	v_mfma_f32_16x16x32_bf16 v[46:49], v[134:137], v[174:177], v[46:49]
	v_mfma_f32_16x16x32_bf16 v[46:49], v[130:133], v[170:173], v[46:49]
	v_mfma_f32_16x16x32_bf16 v[28:31], v[130:133], v[188:191], v[28:31]
	v_mfma_f32_16x16x32_bf16 v[28:31], v[134:137], v[192:195], v[28:31]
	v_mfma_f32_16x16x32_bf16 v[24:27], v[142:145], v[192:195], v[24:27]
	v_mfma_f32_16x16x32_bf16 v[24:27], v[138:141], v[188:191], v[24:27]
	v_mfma_f32_16x16x32_bf16 v[8:11], v[138:141], v[196:199], v[8:11]
	v_mfma_f32_16x16x32_bf16 v[8:11], v[142:145], v[200:203], v[8:11]
	v_mfma_f32_16x16x32_bf16 v[12:15], v[134:137], v[200:203], v[12:15]
	v_mfma_f32_16x16x32_bf16 v[12:15], v[130:133], v[196:199], v[12:15]
	v_mfma_f32_16x16x32_bf16 v[54:57], v[146:149], v[162:165], v[54:57]
	v_mfma_f32_16x16x32_bf16 v[54:57], v[150:153], v[166:169], v[54:57]
	v_mfma_f32_16x16x32_bf16 v[50:53], v[158:161], v[166:169], v[50:53]
	v_mfma_f32_16x16x32_bf16 v[50:53], v[154:157], v[162:165], v[50:53]
	v_mfma_f32_16x16x32_bf16 v[34:37], v[154:157], v[170:173], v[34:37]
	v_mfma_f32_16x16x32_bf16 v[34:37], v[158:161], v[174:177], v[34:37]
	v_mfma_f32_16x16x32_bf16 v[38:41], v[150:153], v[174:177], v[38:41]
	v_mfma_f32_16x16x32_bf16 v[38:41], v[146:149], v[170:173], v[38:41]
	v_mfma_f32_16x16x32_bf16 v[20:23], v[146:149], v[188:191], v[20:23]
	v_mfma_f32_16x16x32_bf16 v[20:23], v[150:153], v[192:195], v[20:23]
	v_mfma_f32_16x16x32_bf16 v[16:19], v[158:161], v[192:195], v[16:19]
	v_mfma_f32_16x16x32_bf16 v[16:19], v[154:157], v[188:191], v[16:19]
	v_mfma_f32_16x16x32_bf16 v[0:3], v[154:157], v[196:199], v[0:3]
	v_mfma_f32_16x16x32_bf16 v[0:3], v[158:161], v[200:203], v[0:3]
	v_mfma_f32_16x16x32_bf16 v[4:7], v[150:153], v[200:203], v[4:7]
	v_mfma_f32_16x16x32_bf16 v[4:7], v[146:149], v[196:199], v[4:7]
	s_setprio 0
	s_barrier
	s_add_i32 s54, 0, 0x18000
	s_add_i32 s55, 0, 0x1c000
	v_add_u32_e32 v142, s54, v212
	v_add_u32_e32 v158, s55, v212
	ds_read_b128 v[130:133], v142
	ds_read_b128 v[134:137], v142 offset:1024
	ds_read_b128 v[138:141], v142 offset:2048
	ds_read_b128 v[142:145], v142 offset:3072
	ds_read_b128 v[146:149], v158
	ds_read_b128 v[150:153], v158 offset:1024
	ds_read_b128 v[154:157], v158 offset:2048
	ds_read_b128 v[158:161], v158 offset:3072
	s_add_u32 s28, s28, 0x80000
	s_addc_u32 s29, s29, 0
	s_mov_b32 m0, s33
	v_lshl_add_u64 v[216:217], s[28:29], 0, v[178:179]
	ds_read_b128 v[162:165], v213 offset:32768
	ds_read_b128 v[166:169], v213 offset:33792
	ds_read_b128 v[170:173], v213 offset:34816
	ds_read_b128 v[174:177], v213 offset:35840
	ds_read_b128 v[188:191], v213 offset:36864
	ds_read_b128 v[192:195], v213 offset:37888
	ds_read_b128 v[196:199], v213 offset:38912
	ds_read_b128 v[200:203], v213 offset:39936
	global_load_lds_dwordx4 v[216:217], off
	v_lshl_add_u64 v[216:217], s[28:29], 0, v[180:181]
	s_mov_b32 m0, s36
	s_nop 0
	global_load_lds_dwordx4 v[216:217], off
	s_waitcnt vmcnt(8)
	s_waitcnt lgkmcnt(0)
	s_barrier
	s_setprio 1
	v_mfma_f32_16x16x32_bf16 v[126:129], v[130:133], v[162:165], v[126:129]
	v_mfma_f32_16x16x32_bf16 v[126:129], v[134:137], v[166:169], v[126:129]
	v_mfma_f32_16x16x32_bf16 v[122:125], v[142:145], v[166:169], v[122:125]
	v_mfma_f32_16x16x32_bf16 v[122:125], v[138:141], v[162:165], v[122:125]
	v_mfma_f32_16x16x32_bf16 v[106:109], v[138:141], v[170:173], v[106:109]
	v_mfma_f32_16x16x32_bf16 v[106:109], v[142:145], v[174:177], v[106:109]
	v_mfma_f32_16x16x32_bf16 v[110:113], v[134:137], v[174:177], v[110:113]
	v_mfma_f32_16x16x32_bf16 v[110:113], v[130:133], v[170:173], v[110:113]
	v_mfma_f32_16x16x32_bf16 v[94:97], v[130:133], v[188:191], v[94:97]
	v_mfma_f32_16x16x32_bf16 v[94:97], v[134:137], v[192:195], v[94:97]
	v_mfma_f32_16x16x32_bf16 v[90:93], v[142:145], v[192:195], v[90:93]
	v_mfma_f32_16x16x32_bf16 v[90:93], v[138:141], v[188:191], v[90:93]
	v_mfma_f32_16x16x32_bf16 v[74:77], v[138:141], v[196:199], v[74:77]
	v_mfma_f32_16x16x32_bf16 v[74:77], v[142:145], v[200:203], v[74:77]
	v_mfma_f32_16x16x32_bf16 v[78:81], v[134:137], v[200:203], v[78:81]
	v_mfma_f32_16x16x32_bf16 v[78:81], v[130:133], v[196:199], v[78:81]
	v_mfma_f32_16x16x32_bf16 v[118:121], v[146:149], v[162:165], v[118:121]
	v_mfma_f32_16x16x32_bf16 v[118:121], v[150:153], v[166:169], v[118:121]
	v_mfma_f32_16x16x32_bf16 v[114:117], v[158:161], v[166:169], v[114:117]
	v_mfma_f32_16x16x32_bf16 v[114:117], v[154:157], v[162:165], v[114:117]
	v_mfma_f32_16x16x32_bf16 v[98:101], v[154:157], v[170:173], v[98:101]
	v_mfma_f32_16x16x32_bf16 v[98:101], v[158:161], v[174:177], v[98:101]
	v_mfma_f32_16x16x32_bf16 v[102:105], v[150:153], v[174:177], v[102:105]
	v_mfma_f32_16x16x32_bf16 v[102:105], v[146:149], v[170:173], v[102:105]
	v_mfma_f32_16x16x32_bf16 v[86:89], v[146:149], v[188:191], v[86:89]
	v_mfma_f32_16x16x32_bf16 v[86:89], v[150:153], v[192:195], v[86:89]
	v_mfma_f32_16x16x32_bf16 v[82:85], v[158:161], v[192:195], v[82:85]
	v_mfma_f32_16x16x32_bf16 v[82:85], v[154:157], v[188:191], v[82:85]
	v_mfma_f32_16x16x32_bf16 v[66:69], v[154:157], v[196:199], v[66:69]
	v_mfma_f32_16x16x32_bf16 v[66:69], v[158:161], v[200:203], v[66:69]
	v_mfma_f32_16x16x32_bf16 v[70:73], v[150:153], v[200:203], v[70:73]
	v_mfma_f32_16x16x32_bf16 v[70:73], v[146:149], v[196:199], v[70:73]
	s_setprio 0
	s_barrier
	s_add_i32 s28, s54, s1
	v_lshl_add_u64 v[204:205], v[204:205], 0, s[34:35]
	s_mov_b32 m0, s28
	ds_read_b128 v[162:165], v213 offset:49152
	ds_read_b128 v[166:169], v213 offset:50176
	ds_read_b128 v[170:173], v213 offset:51200
	ds_read_b128 v[174:177], v213 offset:52224
	ds_read_b128 v[188:191], v213 offset:53248
	ds_read_b128 v[192:195], v213 offset:54272
	ds_read_b128 v[196:199], v213 offset:55296
	ds_read_b128 v[200:203], v213 offset:56320
	global_load_lds_dwordx4 v[204:205], off
	s_add_i32 m0, s28, 0x2000
	s_add_u32 s28, s42, 0x80080
	v_lshl_add_u64 v[204:205], v[206:207], 0, s[34:35]
	s_addc_u32 s29, s43, 0
	s_add_i32 s42, s55, s1
	global_load_lds_dwordx4 v[204:205], off
	v_lshl_add_u64 v[204:205], s[28:29], 0, v[32:33]
	s_mov_b32 m0, s42
	s_nop 0
	global_load_lds_dwordx4 v[204:205], off
	v_lshl_add_u64 v[204:205], s[28:29], 0, v[182:183]
	s_add_i32 m0, s42, 0x2000
	s_nop 0
	global_load_lds_dwordx4 v[204:205], off
	v_lshl_add_u64 v[204:205], v[208:209], 0, s[34:35]
	s_mov_b32 m0, s44
	s_nop 0
	global_load_lds_dwordx4 v[204:205], off
	v_lshl_add_u64 v[204:205], v[214:215], 0, s[34:35]
	s_mov_b32 m0, s45
	s_nop 0
	global_load_lds_dwordx4 v[204:205], off
	s_waitcnt vmcnt(8)
	s_waitcnt lgkmcnt(0)
	s_barrier
	s_setprio 1
	v_mfma_f32_16x16x32_bf16 v[62:65], v[130:133], v[162:165], v[62:65]
	v_mfma_f32_16x16x32_bf16 v[62:65], v[134:137], v[166:169], v[62:65]
	v_mfma_f32_16x16x32_bf16 v[58:61], v[142:145], v[166:169], v[58:61]
	v_mfma_f32_16x16x32_bf16 v[58:61], v[138:141], v[162:165], v[58:61]
	v_mfma_f32_16x16x32_bf16 v[42:45], v[138:141], v[170:173], v[42:45]
	v_mfma_f32_16x16x32_bf16 v[42:45], v[142:145], v[174:177], v[42:45]
	v_mfma_f32_16x16x32_bf16 v[46:49], v[134:137], v[174:177], v[46:49]
	v_mfma_f32_16x16x32_bf16 v[46:49], v[130:133], v[170:173], v[46:49]
	v_mfma_f32_16x16x32_bf16 v[28:31], v[130:133], v[188:191], v[28:31]
	v_mfma_f32_16x16x32_bf16 v[28:31], v[134:137], v[192:195], v[28:31]
	v_mfma_f32_16x16x32_bf16 v[24:27], v[142:145], v[192:195], v[24:27]
	v_mfma_f32_16x16x32_bf16 v[24:27], v[138:141], v[188:191], v[24:27]
	v_mfma_f32_16x16x32_bf16 v[8:11], v[138:141], v[196:199], v[8:11]
	v_mfma_f32_16x16x32_bf16 v[8:11], v[142:145], v[200:203], v[8:11]
	v_mfma_f32_16x16x32_bf16 v[12:15], v[134:137], v[200:203], v[12:15]
	v_mfma_f32_16x16x32_bf16 v[12:15], v[130:133], v[196:199], v[12:15]
	v_mfma_f32_16x16x32_bf16 v[54:57], v[146:149], v[162:165], v[54:57]
	v_mfma_f32_16x16x32_bf16 v[54:57], v[150:153], v[166:169], v[54:57]
	v_mfma_f32_16x16x32_bf16 v[50:53], v[158:161], v[166:169], v[50:53]
	v_mfma_f32_16x16x32_bf16 v[50:53], v[154:157], v[162:165], v[50:53]
	v_mfma_f32_16x16x32_bf16 v[34:37], v[154:157], v[170:173], v[34:37]
	v_mfma_f32_16x16x32_bf16 v[34:37], v[158:161], v[174:177], v[34:37]
	v_mfma_f32_16x16x32_bf16 v[38:41], v[150:153], v[174:177], v[38:41]
	v_mfma_f32_16x16x32_bf16 v[38:41], v[146:149], v[170:173], v[38:41]
	v_mfma_f32_16x16x32_bf16 v[20:23], v[146:149], v[188:191], v[20:23]
	v_mfma_f32_16x16x32_bf16 v[20:23], v[150:153], v[192:195], v[20:23]
	v_mfma_f32_16x16x32_bf16 v[16:19], v[158:161], v[192:195], v[16:19]
	v_mfma_f32_16x16x32_bf16 v[16:19], v[154:157], v[188:191], v[16:19]
	v_mfma_f32_16x16x32_bf16 v[0:3], v[154:157], v[196:199], v[0:3]
	v_mfma_f32_16x16x32_bf16 v[0:3], v[158:161], v[200:203], v[0:3]
	v_mfma_f32_16x16x32_bf16 v[4:7], v[150:153], v[200:203], v[4:7]
	v_mfma_f32_16x16x32_bf16 v[4:7], v[146:149], v[196:199], v[4:7]
	s_setprio 0
	s_barrier
	s_add_i32 s53, s53, 2
	s_add_u32 s40, s40, 0x100
	s_addc_u32 s41, s41, 0
	s_add_u32 s51, s51, 0x100
	s_addc_u32 s52, s52, 0
	s_cmp_gt_u32 s53, 29
	s_cbranch_scc0 .LBB0_120
	s_and_b64 vcc, exec, s[18:19]
	s_cbranch_vccz .LBB0_123
	s_barrier

.LBB0_685:
	s_add_u32 s28, s16, s40
	s_addc_u32 s29, s17, s41
	s_add_u32 s28, s28, 0x100
	s_addc_u32 s29, s29, 0
	s_add_u32 s42, s52, s40
	s_addc_u32 s43, s53, s41
	s_add_i32 s56, 0, 0x10000
	s_cmpk_eq_i32 s40, 0xf00
	s_cselect_b32 s29, s39, s29
	s_cselect_b32 s28, s38, s28
	s_cselect_b32 s43, s23, s43
	s_cselect_b32 s42, s54, s42
	s_add_i32 s58, 0, 0x14000
	v_add_u32_e32 v146, s56, v190
	v_add_u32_e32 v162, s58, v190
	ds_read_b128 v[134:137], v146
	ds_read_b128 v[138:141], v146 offset:1024
	ds_read_b128 v[142:145], v146 offset:2048
	ds_read_b128 v[146:149], v146 offset:3072
	ds_read_b128 v[150:153], v162
	ds_read_b128 v[154:157], v162 offset:1024
	ds_read_b128 v[158:161], v162 offset:2048
	ds_read_b128 v[162:165], v162 offset:3072
	v_lshl_add_u64 v[212:213], v[130:131], 0, s[40:41]
	s_add_i32 m0, s24, 0xc000
	ds_read_b128 v[166:169], v191
	ds_read_b128 v[180:183], v191 offset:1024
	ds_read_b128 v[184:187], v191 offset:2048
	ds_read_b128 v[192:195], v191 offset:3072
	ds_read_b128 v[196:199], v191 offset:4096
	ds_read_b128 v[200:203], v191 offset:5120
	ds_read_b128 v[204:207], v191 offset:6144
	ds_read_b128 v[208:211], v191 offset:7168
	global_load_lds_dwordx4 v[212:213], off
	v_lshl_add_u64 v[212:213], v[132:133], 0, s[40:41]
	s_add_i32 m0, s24, 0xe000
	s_nop 0
	global_load_lds_dwordx4 v[212:213], off
	s_waitcnt vmcnt(8)
	s_waitcnt lgkmcnt(0)
	s_barrier
	s_setprio 1
	v_mfma_f32_16x16x32_bf16 v[82:85], v[134:137], v[166:169], v[82:85]
	v_mfma_f32_16x16x32_bf16 v[82:85], v[138:141], v[180:183], v[82:85]
	v_mfma_f32_16x16x32_bf16 v[78:81], v[146:149], v[180:183], v[78:81]
	v_mfma_f32_16x16x32_bf16 v[78:81], v[142:145], v[166:169], v[78:81]
	v_mfma_f32_16x16x32_bf16 v[70:73], v[142:145], v[184:187], v[70:73]
	v_mfma_f32_16x16x32_bf16 v[70:73], v[146:149], v[192:195], v[70:73]
	v_mfma_f32_16x16x32_bf16 v[74:77], v[138:141], v[192:195], v[74:77]
	v_mfma_f32_16x16x32_bf16 v[74:77], v[134:137], v[184:187], v[74:77]
	v_mfma_f32_16x16x32_bf16 v[66:69], v[134:137], v[196:199], v[66:69]
	v_mfma_f32_16x16x32_bf16 v[66:69], v[138:141], v[200:203], v[66:69]
	v_mfma_f32_16x16x32_bf16 v[62:65], v[146:149], v[200:203], v[62:65]
	v_mfma_f32_16x16x32_bf16 v[62:65], v[142:145], v[196:199], v[62:65]
	v_mfma_f32_16x16x32_bf16 v[54:57], v[142:145], v[204:207], v[54:57]
	v_mfma_f32_16x16x32_bf16 v[54:57], v[146:149], v[208:211], v[54:57]
	v_mfma_f32_16x16x32_bf16 v[58:61], v[138:141], v[208:211], v[58:61]
	v_mfma_f32_16x16x32_bf16 v[58:61], v[134:137], v[204:207], v[58:61]
	v_mfma_f32_16x16x32_bf16 v[50:53], v[150:153], v[166:169], v[50:53]
	v_mfma_f32_16x16x32_bf16 v[50:53], v[154:157], v[180:183], v[50:53]
	v_mfma_f32_16x16x32_bf16 v[46:49], v[162:165], v[180:183], v[46:49]
	v_mfma_f32_16x16x32_bf16 v[46:49], v[158:161], v[166:169], v[46:49]
	v_mfma_f32_16x16x32_bf16 v[38:41], v[158:161], v[184:187], v[38:41]
	v_mfma_f32_16x16x32_bf16 v[38:41], v[162:165], v[192:195], v[38:41]
	v_mfma_f32_16x16x32_bf16 v[42:45], v[154:157], v[192:195], v[42:45]
	v_mfma_f32_16x16x32_bf16 v[42:45], v[150:153], v[184:187], v[42:45]
	v_mfma_f32_16x16x32_bf16 v[34:37], v[150:153], v[196:199], v[34:37]
	v_mfma_f32_16x16x32_bf16 v[34:37], v[154:157], v[200:203], v[34:37]
	v_mfma_f32_16x16x32_bf16 v[28:31], v[162:165], v[200:203], v[28:31]
	v_mfma_f32_16x16x32_bf16 v[28:31], v[158:161], v[196:199], v[28:31]
	v_mfma_f32_16x16x32_bf16 v[20:23], v[158:161], v[204:207], v[20:23]
	v_mfma_f32_16x16x32_bf16 v[20:23], v[162:165], v[208:211], v[20:23]
	v_mfma_f32_16x16x32_bf16 v[24:27], v[154:157], v[208:211], v[24:27]
	v_mfma_f32_16x16x32_bf16 v[24:27], v[150:153], v[204:207], v[24:27]
	s_setprio 0
	s_barrier
	s_add_i32 s56, s56, s13
	v_lshl_add_u64 v[212:213], s[42:43], 0, v[32:33]
	s_mov_b32 m0, s56
	ds_read_b128 v[166:169], v191 offset:16384
	ds_read_b128 v[180:183], v191 offset:17408
	ds_read_b128 v[184:187], v191 offset:18432
	ds_read_b128 v[192:195], v191 offset:19456
	ds_read_b128 v[196:199], v191 offset:20480
	ds_read_b128 v[200:203], v191 offset:21504
	ds_read_b128 v[204:207], v191 offset:22528
	ds_read_b128 v[208:211], v191 offset:23552
	global_load_lds_dwordx4 v[212:213], off
	s_add_i32 m0, s56, 0x2000
	s_add_u32 s56, s42, 0x80000
	v_lshl_add_u64 v[214:215], s[42:43], 0, v[174:175]
	s_addc_u32 s57, s43, 0
	s_add_i32 s58, s58, s13
	global_load_lds_dwordx4 v[214:215], off
	v_lshl_add_u64 v[216:217], s[56:57], 0, v[32:33]
	s_mov_b32 m0, s58
	v_lshl_add_u64 v[220:221], s[28:29], 0, v[172:173]
	global_load_lds_dwordx4 v[216:217], off
	v_lshl_add_u64 v[216:217], s[56:57], 0, v[174:175]
	s_add_i32 m0, s58, 0x2000
	s_nop 0
	global_load_lds_dwordx4 v[216:217], off
	v_lshl_add_u64 v[216:217], s[28:29], 0, v[170:171]
	s_mov_b32 m0, s24
	s_nop 0
	global_load_lds_dwordx4 v[216:217], off
	s_mov_b32 m0, s25
	s_nop 0
	global_load_lds_dwordx4 v[220:221], off
	s_waitcnt vmcnt(8)
	s_waitcnt lgkmcnt(0)
	s_barrier
	s_setprio 1
	v_mfma_f32_16x16x32_bf16 v[16:19], v[134:137], v[166:169], v[16:19]
	v_mfma_f32_16x16x32_bf16 v[16:19], v[138:141], v[180:183], v[16:19]
	v_mfma_f32_16x16x32_bf16 v[12:15], v[146:149], v[180:183], v[12:15]
	v_mfma_f32_16x16x32_bf16 v[12:15], v[142:145], v[166:169], v[12:15]
	v_mfma_f32_16x16x32_bf16 v[4:7], v[142:145], v[184:187], v[4:7]
	v_mfma_f32_16x16x32_bf16 v[4:7], v[146:149], v[192:195], v[4:7]
	v_mfma_f32_16x16x32_bf16 v[8:11], v[138:141], v[192:195], v[8:11]
	v_mfma_f32_16x16x32_bf16 v[8:11], v[134:137], v[184:187], v[8:11]
	v_mfma_f32_16x16x32_bf16 v[0:3], v[134:137], v[196:199], v[0:3]
	v_mfma_f32_16x16x32_bf16 v[0:3], v[138:141], v[200:203], v[0:3]
	v_mfma_f32_16x16x32_bf16 v[86:89], v[146:149], v[200:203], v[86:89]
	v_mfma_f32_16x16x32_bf16 v[86:89], v[142:145], v[196:199], v[86:89]
	v_mfma_f32_16x16x32_bf16 v[94:97], v[142:145], v[204:207], v[94:97]
	v_mfma_f32_16x16x32_bf16 v[94:97], v[146:149], v[208:211], v[94:97]
	v_mfma_f32_16x16x32_bf16 v[90:93], v[138:141], v[208:211], v[90:93]
	v_mfma_f32_16x16x32_bf16 v[90:93], v[134:137], v[204:207], v[90:93]
	v_mfma_f32_16x16x32_bf16 v[98:101], v[150:153], v[166:169], v[98:101]
	v_mfma_f32_16x16x32_bf16 v[98:101], v[154:157], v[180:183], v[98:101]
	v_mfma_f32_16x16x32_bf16 v[102:105], v[162:165], v[180:183], v[102:105]
	v_mfma_f32_16x16x32_bf16 v[102:105], v[158:161], v[166:169], v[102:105]
	v_mfma_f32_16x16x32_bf16 v[110:113], v[158:161], v[184:187], v[110:113]
	v_mfma_f32_16x16x32_bf16 v[110:113], v[162:165], v[192:195], v[110:113]
	v_mfma_f32_16x16x32_bf16 v[106:109], v[154:157], v[192:195], v[106:109]
	v_mfma_f32_16x16x32_bf16 v[106:109], v[150:153], v[184:187], v[106:109]
	v_mfma_f32_16x16x32_bf16 v[114:117], v[150:153], v[196:199], v[114:117]
	v_mfma_f32_16x16x32_bf16 v[114:117], v[154:157], v[200:203], v[114:117]
	v_mfma_f32_16x16x32_bf16 v[118:121], v[162:165], v[200:203], v[118:121]
	v_mfma_f32_16x16x32_bf16 v[118:121], v[158:161], v[196:199], v[118:121]
	v_mfma_f32_16x16x32_bf16 v[126:129], v[158:161], v[204:207], v[126:129]
	v_mfma_f32_16x16x32_bf16 v[126:129], v[162:165], v[208:211], v[126:129]
	v_mfma_f32_16x16x32_bf16 v[122:125], v[154:157], v[208:211], v[122:125]
	v_mfma_f32_16x16x32_bf16 v[122:125], v[150:153], v[204:207], v[122:125]
	s_setprio 0
	s_barrier
	s_add_i32 s56, 0, 0x18000
	s_add_i32 s57, 0, 0x1c000
	v_add_u32_e32 v146, s56, v190
	v_add_u32_e32 v162, s57, v190
	ds_read_b128 v[134:137], v146
	ds_read_b128 v[138:141], v146 offset:1024
	ds_read_b128 v[142:145], v146 offset:2048
	ds_read_b128 v[146:149], v146 offset:3072
	ds_read_b128 v[150:153], v162
	ds_read_b128 v[154:157], v162 offset:1024
	ds_read_b128 v[158:161], v162 offset:2048
	ds_read_b128 v[162:165], v162 offset:3072
	s_add_u32 s28, s28, 0x80000
	s_addc_u32 s29, s29, 0
	s_mov_b32 m0, s33
	v_lshl_add_u64 v[222:223], s[28:29], 0, v[170:171]
	ds_read_b128 v[166:169], v191 offset:32768
	ds_read_b128 v[180:183], v191 offset:33792
	ds_read_b128 v[184:187], v191 offset:34816
	ds_read_b128 v[192:195], v191 offset:35840
	ds_read_b128 v[196:199], v191 offset:36864
	ds_read_b128 v[200:203], v191 offset:37888
	ds_read_b128 v[204:207], v191 offset:38912
	ds_read_b128 v[208:211], v191 offset:39936
	global_load_lds_dwordx4 v[222:223], off
	v_lshl_add_u64 v[222:223], s[28:29], 0, v[172:173]
	s_mov_b32 m0, s36
	s_nop 0
	global_load_lds_dwordx4 v[222:223], off
	s_waitcnt vmcnt(8)
	s_waitcnt lgkmcnt(0)
	s_barrier
	s_setprio 1
	v_mfma_f32_16x16x32_bf16 v[82:85], v[134:137], v[166:169], v[82:85]
	v_mfma_f32_16x16x32_bf16 v[82:85], v[138:141], v[180:183], v[82:85]
	v_mfma_f32_16x16x32_bf16 v[78:81], v[146:149], v[180:183], v[78:81]
	v_mfma_f32_16x16x32_bf16 v[78:81], v[142:145], v[166:169], v[78:81]
	v_mfma_f32_16x16x32_bf16 v[70:73], v[142:145], v[184:187], v[70:73]
	v_mfma_f32_16x16x32_bf16 v[70:73], v[146:149], v[192:195], v[70:73]
	v_mfma_f32_16x16x32_bf16 v[74:77], v[138:141], v[192:195], v[74:77]
	v_mfma_f32_16x16x32_bf16 v[74:77], v[134:137], v[184:187], v[74:77]
	v_mfma_f32_16x16x32_bf16 v[66:69], v[134:137], v[196:199], v[66:69]
	v_mfma_f32_16x16x32_bf16 v[66:69], v[138:141], v[200:203], v[66:69]
	v_mfma_f32_16x16x32_bf16 v[62:65], v[146:149], v[200:203], v[62:65]
	v_mfma_f32_16x16x32_bf16 v[62:65], v[142:145], v[196:199], v[62:65]
	v_mfma_f32_16x16x32_bf16 v[54:57], v[142:145], v[204:207], v[54:57]
	v_mfma_f32_16x16x32_bf16 v[54:57], v[146:149], v[208:211], v[54:57]
	v_mfma_f32_16x16x32_bf16 v[58:61], v[138:141], v[208:211], v[58:61]
	v_mfma_f32_16x16x32_bf16 v[58:61], v[134:137], v[204:207], v[58:61]
	v_mfma_f32_16x16x32_bf16 v[50:53], v[150:153], v[166:169], v[50:53]
	v_mfma_f32_16x16x32_bf16 v[50:53], v[154:157], v[180:183], v[50:53]
	v_mfma_f32_16x16x32_bf16 v[46:49], v[162:165], v[180:183], v[46:49]
	v_mfma_f32_16x16x32_bf16 v[46:49], v[158:161], v[166:169], v[46:49]
	v_mfma_f32_16x16x32_bf16 v[38:41], v[158:161], v[184:187], v[38:41]
	v_mfma_f32_16x16x32_bf16 v[38:41], v[162:165], v[192:195], v[38:41]
	v_mfma_f32_16x16x32_bf16 v[42:45], v[154:157], v[192:195], v[42:45]
	v_mfma_f32_16x16x32_bf16 v[42:45], v[150:153], v[184:187], v[42:45]
	v_mfma_f32_16x16x32_bf16 v[34:37], v[150:153], v[196:199], v[34:37]
	v_mfma_f32_16x16x32_bf16 v[34:37], v[154:157], v[200:203], v[34:37]
	v_mfma_f32_16x16x32_bf16 v[28:31], v[162:165], v[200:203], v[28:31]
	v_mfma_f32_16x16x32_bf16 v[28:31], v[158:161], v[196:199], v[28:31]
	v_mfma_f32_16x16x32_bf16 v[20:23], v[158:161], v[204:207], v[20:23]
	v_mfma_f32_16x16x32_bf16 v[20:23], v[162:165], v[208:211], v[20:23]
	v_mfma_f32_16x16x32_bf16 v[24:27], v[154:157], v[208:211], v[24:27]
	v_mfma_f32_16x16x32_bf16 v[24:27], v[150:153], v[204:207], v[24:27]
	s_setprio 0
	s_barrier
	s_add_i32 s28, s56, s13
	v_lshl_add_u64 v[212:213], v[212:213], 0, s[34:35]
	s_mov_b32 m0, s28
	ds_read_b128 v[166:169], v191 offset:49152
	ds_read_b128 v[180:183], v191 offset:50176
	ds_read_b128 v[184:187], v191 offset:51200
	ds_read_b128 v[192:195], v191 offset:52224
	ds_read_b128 v[196:199], v191 offset:53248
	ds_read_b128 v[200:203], v191 offset:54272
	ds_read_b128 v[204:207], v191 offset:55296
	ds_read_b128 v[208:211], v191 offset:56320
	global_load_lds_dwordx4 v[212:213], off
	s_add_i32 m0, s28, 0x2000
	s_add_u32 s28, s42, 0x80080
	v_lshl_add_u64 v[212:213], v[214:215], 0, s[34:35]
	s_addc_u32 s29, s43, 0
	s_add_i32 s42, s57, s13
	global_load_lds_dwordx4 v[212:213], off
	v_lshl_add_u64 v[212:213], s[28:29], 0, v[32:33]
	s_mov_b32 m0, s42
	s_nop 0
	global_load_lds_dwordx4 v[212:213], off
	v_lshl_add_u64 v[212:213], s[28:29], 0, v[174:175]
	s_add_i32 m0, s42, 0x2000
	s_nop 0
	global_load_lds_dwordx4 v[212:213], off
	v_lshl_add_u64 v[212:213], v[216:217], 0, s[34:35]
	s_mov_b32 m0, s45
	s_nop 0
	global_load_lds_dwordx4 v[212:213], off
	v_lshl_add_u64 v[212:213], v[220:221], 0, s[34:35]
	s_mov_b32 m0, s46
	s_nop 0
	global_load_lds_dwordx4 v[212:213], off
	s_waitcnt vmcnt(8)
	s_waitcnt lgkmcnt(0)
	s_barrier
	s_setprio 1
	v_mfma_f32_16x16x32_bf16 v[16:19], v[134:137], v[166:169], v[16:19]
	v_mfma_f32_16x16x32_bf16 v[16:19], v[138:141], v[180:183], v[16:19]
	v_mfma_f32_16x16x32_bf16 v[12:15], v[146:149], v[180:183], v[12:15]
	v_mfma_f32_16x16x32_bf16 v[12:15], v[142:145], v[166:169], v[12:15]
	v_mfma_f32_16x16x32_bf16 v[4:7], v[142:145], v[184:187], v[4:7]
	v_mfma_f32_16x16x32_bf16 v[4:7], v[146:149], v[192:195], v[4:7]
	v_mfma_f32_16x16x32_bf16 v[8:11], v[138:141], v[192:195], v[8:11]
	v_mfma_f32_16x16x32_bf16 v[8:11], v[134:137], v[184:187], v[8:11]
	v_mfma_f32_16x16x32_bf16 v[0:3], v[134:137], v[196:199], v[0:3]
	v_mfma_f32_16x16x32_bf16 v[0:3], v[138:141], v[200:203], v[0:3]
	v_mfma_f32_16x16x32_bf16 v[86:89], v[146:149], v[200:203], v[86:89]
	v_mfma_f32_16x16x32_bf16 v[86:89], v[142:145], v[196:199], v[86:89]
	v_mfma_f32_16x16x32_bf16 v[94:97], v[142:145], v[204:207], v[94:97]
	v_mfma_f32_16x16x32_bf16 v[94:97], v[146:149], v[208:211], v[94:97]
	v_mfma_f32_16x16x32_bf16 v[90:93], v[138:141], v[208:211], v[90:93]
	v_mfma_f32_16x16x32_bf16 v[90:93], v[134:137], v[204:207], v[90:93]
	v_mfma_f32_16x16x32_bf16 v[98:101], v[150:153], v[166:169], v[98:101]
	v_mfma_f32_16x16x32_bf16 v[98:101], v[154:157], v[180:183], v[98:101]
	v_mfma_f32_16x16x32_bf16 v[102:105], v[162:165], v[180:183], v[102:105]
	v_mfma_f32_16x16x32_bf16 v[102:105], v[158:161], v[166:169], v[102:105]
	v_mfma_f32_16x16x32_bf16 v[110:113], v[158:161], v[184:187], v[110:113]
	v_mfma_f32_16x16x32_bf16 v[110:113], v[162:165], v[192:195], v[110:113]
	v_mfma_f32_16x16x32_bf16 v[106:109], v[154:157], v[192:195], v[106:109]
	v_mfma_f32_16x16x32_bf16 v[106:109], v[150:153], v[184:187], v[106:109]
	v_mfma_f32_16x16x32_bf16 v[114:117], v[150:153], v[196:199], v[114:117]
	v_mfma_f32_16x16x32_bf16 v[114:117], v[154:157], v[200:203], v[114:117]
	v_mfma_f32_16x16x32_bf16 v[118:121], v[162:165], v[200:203], v[118:121]
	v_mfma_f32_16x16x32_bf16 v[118:121], v[158:161], v[196:199], v[118:121]
	v_mfma_f32_16x16x32_bf16 v[126:129], v[158:161], v[204:207], v[126:129]
	v_mfma_f32_16x16x32_bf16 v[126:129], v[162:165], v[208:211], v[126:129]
	v_mfma_f32_16x16x32_bf16 v[122:125], v[154:157], v[208:211], v[122:125]
	v_mfma_f32_16x16x32_bf16 v[122:125], v[150:153], v[204:207], v[122:125]
	s_setprio 0
	s_barrier
	s_add_i32 s55, s55, 2
	s_add_u32 s40, s40, 0x100
	s_addc_u32 s41, s41, 0
	s_cmp_gt_u32 s55, 29
	s_cbranch_scc0 .LBB0_685
	s_and_b64 vcc, exec, s[18:19]
	s_cbranch_vccz .LBB0_688
	s_barrier

.LBB0_755:
	s_add_u32 s6, s4, 0x100
	s_addc_u32 s7, s5, 0
	s_add_i32 s52, 0, 0x10000
	s_cmpk_eq_i32 s51, 0x54
	s_cselect_b32 s29, s23, s7
	s_cselect_b32 s28, s22, s6
	s_cselect_b32 s31, s27, s50
	s_cselect_b32 s30, s26, s33
	s_add_i32 s53, 0, 0x14000
	v_add_u32_e32 v142, s52, v242
	v_add_u32_e32 v158, s53, v242
	ds_read_b128 v[130:133], v142
	ds_read_b128 v[134:137], v142 offset:1024
	ds_read_b128 v[138:141], v142 offset:2048
	ds_read_b128 v[142:145], v142 offset:3072
	ds_read_b128 v[146:149], v158
	ds_read_b128 v[150:153], v158 offset:1024
	ds_read_b128 v[154:157], v158 offset:2048
	ds_read_b128 v[158:161], v158 offset:3072
	v_lshl_add_u64 v[194:195], s[4:5], 0, v[202:203]
	s_add_i32 m0, s36, 0xc000
	ds_read_b128 v[162:165], v243
	ds_read_b128 v[166:169], v243 offset:1024
	ds_read_b128 v[170:173], v243 offset:2048
	ds_read_b128 v[174:177], v243 offset:3072
	ds_read_b128 v[178:181], v243 offset:4096
	ds_read_b128 v[182:185], v243 offset:5120
	ds_read_b128 v[186:189], v243 offset:6144
	ds_read_b128 v[190:193], v243 offset:7168
	global_load_lds_dwordx4 v[194:195], off
	v_lshl_add_u64 v[194:195], s[4:5], 0, v[204:205]
	s_add_i32 m0, s36, 0xe000
	s_nop 0
	global_load_lds_dwordx4 v[194:195], off
	s_waitcnt vmcnt(8)
	s_waitcnt lgkmcnt(0)
	s_barrier
	s_setprio 1
	v_mfma_f32_16x16x32_bf16 v[126:129], v[130:133], v[162:165], v[126:129]
	v_mfma_f32_16x16x32_bf16 v[126:129], v[134:137], v[166:169], v[126:129]
	v_mfma_f32_16x16x32_bf16 v[122:125], v[142:145], v[166:169], v[122:125]
	v_mfma_f32_16x16x32_bf16 v[122:125], v[138:141], v[162:165], v[122:125]
	v_mfma_f32_16x16x32_bf16 v[106:109], v[138:141], v[170:173], v[106:109]
	v_mfma_f32_16x16x32_bf16 v[106:109], v[142:145], v[174:177], v[106:109]
	v_mfma_f32_16x16x32_bf16 v[110:113], v[134:137], v[174:177], v[110:113]
	v_mfma_f32_16x16x32_bf16 v[110:113], v[130:133], v[170:173], v[110:113]
	v_mfma_f32_16x16x32_bf16 v[94:97], v[130:133], v[178:181], v[94:97]
	v_mfma_f32_16x16x32_bf16 v[94:97], v[134:137], v[182:185], v[94:97]
	v_mfma_f32_16x16x32_bf16 v[90:93], v[142:145], v[182:185], v[90:93]
	v_mfma_f32_16x16x32_bf16 v[90:93], v[138:141], v[178:181], v[90:93]
	v_mfma_f32_16x16x32_bf16 v[74:77], v[138:141], v[186:189], v[74:77]
	v_mfma_f32_16x16x32_bf16 v[74:77], v[142:145], v[190:193], v[74:77]
	v_mfma_f32_16x16x32_bf16 v[78:81], v[134:137], v[190:193], v[78:81]
	v_mfma_f32_16x16x32_bf16 v[78:81], v[130:133], v[186:189], v[78:81]
	v_mfma_f32_16x16x32_bf16 v[118:121], v[146:149], v[162:165], v[118:121]
	v_mfma_f32_16x16x32_bf16 v[118:121], v[150:153], v[166:169], v[118:121]
	v_mfma_f32_16x16x32_bf16 v[114:117], v[158:161], v[166:169], v[114:117]
	v_mfma_f32_16x16x32_bf16 v[114:117], v[154:157], v[162:165], v[114:117]
	v_mfma_f32_16x16x32_bf16 v[98:101], v[154:157], v[170:173], v[98:101]
	v_mfma_f32_16x16x32_bf16 v[98:101], v[158:161], v[174:177], v[98:101]
	v_mfma_f32_16x16x32_bf16 v[102:105], v[150:153], v[174:177], v[102:105]
	v_mfma_f32_16x16x32_bf16 v[102:105], v[146:149], v[170:173], v[102:105]
	v_mfma_f32_16x16x32_bf16 v[86:89], v[146:149], v[178:181], v[86:89]
	v_mfma_f32_16x16x32_bf16 v[86:89], v[150:153], v[182:185], v[86:89]
	v_mfma_f32_16x16x32_bf16 v[82:85], v[158:161], v[182:185], v[82:85]
	v_mfma_f32_16x16x32_bf16 v[82:85], v[154:157], v[178:181], v[82:85]
	v_mfma_f32_16x16x32_bf16 v[66:69], v[154:157], v[186:189], v[66:69]
	v_mfma_f32_16x16x32_bf16 v[66:69], v[158:161], v[190:193], v[66:69]
	v_mfma_f32_16x16x32_bf16 v[70:73], v[150:153], v[190:193], v[70:73]
	v_mfma_f32_16x16x32_bf16 v[70:73], v[146:149], v[186:189], v[70:73]
	s_setprio 0
	s_barrier
	s_add_i32 s4, s52, s1
	v_lshl_add_u64 v[194:195], s[30:31], 0, v[32:33]
	s_mov_b32 m0, s4
	ds_read_b128 v[162:165], v243 offset:16384
	ds_read_b128 v[166:169], v243 offset:17408
	ds_read_b128 v[170:173], v243 offset:18432
	ds_read_b128 v[174:177], v243 offset:19456
	ds_read_b128 v[178:181], v243 offset:20480
	ds_read_b128 v[182:185], v243 offset:21504
	ds_read_b128 v[186:189], v243 offset:22528
	ds_read_b128 v[190:193], v243 offset:23552
	global_load_lds_dwordx4 v[194:195], off
	s_add_i32 m0, s4, 0x2000
	s_add_u32 s4, s30, 0x160000
	v_lshl_add_u64 v[206:207], s[30:31], 0, v[200:201]
	s_addc_u32 s5, s31, 0
	s_add_i32 s52, s53, s1
	global_load_lds_dwordx4 v[206:207], off
	v_lshl_add_u64 v[208:209], s[4:5], 0, v[32:33]
	s_mov_b32 m0, s52
	v_lshl_add_u64 v[210:211], s[28:29], 0, v[198:199]
	global_load_lds_dwordx4 v[208:209], off
	v_lshl_add_u64 v[208:209], s[4:5], 0, v[200:201]
	s_add_i32 m0, s52, 0x2000
	s_nop 0
	global_load_lds_dwordx4 v[208:209], off
	v_lshl_add_u64 v[208:209], s[28:29], 0, v[196:197]
	s_mov_b32 m0, s36
	s_nop 0
	global_load_lds_dwordx4 v[208:209], off
	s_mov_b32 m0, s38
	s_nop 0
	global_load_lds_dwordx4 v[210:211], off
	s_waitcnt vmcnt(8)
	s_waitcnt lgkmcnt(0)
	s_barrier
	s_setprio 1
	v_mfma_f32_16x16x32_bf16 v[62:65], v[130:133], v[162:165], v[62:65]
	v_mfma_f32_16x16x32_bf16 v[62:65], v[134:137], v[166:169], v[62:65]
	v_mfma_f32_16x16x32_bf16 v[58:61], v[142:145], v[166:169], v[58:61]
	v_mfma_f32_16x16x32_bf16 v[58:61], v[138:141], v[162:165], v[58:61]
	v_mfma_f32_16x16x32_bf16 v[42:45], v[138:141], v[170:173], v[42:45]
	v_mfma_f32_16x16x32_bf16 v[42:45], v[142:145], v[174:177], v[42:45]
	v_mfma_f32_16x16x32_bf16 v[46:49], v[134:137], v[174:177], v[46:49]
	v_mfma_f32_16x16x32_bf16 v[46:49], v[130:133], v[170:173], v[46:49]
	v_mfma_f32_16x16x32_bf16 v[28:31], v[130:133], v[178:181], v[28:31]
	v_mfma_f32_16x16x32_bf16 v[28:31], v[134:137], v[182:185], v[28:31]
	v_mfma_f32_16x16x32_bf16 v[24:27], v[142:145], v[182:185], v[24:27]
	v_mfma_f32_16x16x32_bf16 v[24:27], v[138:141], v[178:181], v[24:27]
	v_mfma_f32_16x16x32_bf16 v[8:11], v[138:141], v[186:189], v[8:11]
	v_mfma_f32_16x16x32_bf16 v[8:11], v[142:145], v[190:193], v[8:11]
	v_mfma_f32_16x16x32_bf16 v[12:15], v[134:137], v[190:193], v[12:15]
	v_mfma_f32_16x16x32_bf16 v[12:15], v[130:133], v[186:189], v[12:15]
	v_mfma_f32_16x16x32_bf16 v[54:57], v[146:149], v[162:165], v[54:57]
	v_mfma_f32_16x16x32_bf16 v[54:57], v[150:153], v[166:169], v[54:57]
	v_mfma_f32_16x16x32_bf16 v[50:53], v[158:161], v[166:169], v[50:53]
	v_mfma_f32_16x16x32_bf16 v[50:53], v[154:157], v[162:165], v[50:53]
	v_mfma_f32_16x16x32_bf16 v[34:37], v[154:157], v[170:173], v[34:37]
	v_mfma_f32_16x16x32_bf16 v[34:37], v[158:161], v[174:177], v[34:37]
	v_mfma_f32_16x16x32_bf16 v[38:41], v[150:153], v[174:177], v[38:41]
	v_mfma_f32_16x16x32_bf16 v[38:41], v[146:149], v[170:173], v[38:41]
	v_mfma_f32_16x16x32_bf16 v[20:23], v[146:149], v[178:181], v[20:23]
	v_mfma_f32_16x16x32_bf16 v[20:23], v[150:153], v[182:185], v[20:23]
	v_mfma_f32_16x16x32_bf16 v[16:19], v[158:161], v[182:185], v[16:19]
	v_mfma_f32_16x16x32_bf16 v[16:19], v[154:157], v[178:181], v[16:19]
	v_mfma_f32_16x16x32_bf16 v[0:3], v[154:157], v[186:189], v[0:3]
	v_mfma_f32_16x16x32_bf16 v[0:3], v[158:161], v[190:193], v[0:3]
	v_mfma_f32_16x16x32_bf16 v[4:7], v[150:153], v[190:193], v[4:7]
	v_mfma_f32_16x16x32_bf16 v[4:7], v[146:149], v[186:189], v[4:7]
	s_setprio 0
	s_barrier
	s_add_i32 s52, 0, 0x18000
	s_add_i32 s53, 0, 0x1c000
	v_add_u32_e32 v142, s52, v242
	v_add_u32_e32 v158, s53, v242
	ds_read_b128 v[130:133], v142
	ds_read_b128 v[134:137], v142 offset:1024
	ds_read_b128 v[138:141], v142 offset:2048
	ds_read_b128 v[142:145], v142 offset:3072
	ds_read_b128 v[146:149], v158
	ds_read_b128 v[150:153], v158 offset:1024
	ds_read_b128 v[154:157], v158 offset:2048
	ds_read_b128 v[158:161], v158 offset:3072
	s_add_u32 s4, s28, 0x160000
	s_addc_u32 s5, s29, 0
	s_mov_b32 m0, s39
	v_lshl_add_u64 v[212:213], s[4:5], 0, v[196:197]
	ds_read_b128 v[162:165], v243 offset:32768
	ds_read_b128 v[166:169], v243 offset:33792
	ds_read_b128 v[170:173], v243 offset:34816
	ds_read_b128 v[174:177], v243 offset:35840
	ds_read_b128 v[178:181], v243 offset:36864
	ds_read_b128 v[182:185], v243 offset:37888
	ds_read_b128 v[186:189], v243 offset:38912
	ds_read_b128 v[190:193], v243 offset:39936
	global_load_lds_dwordx4 v[212:213], off
	v_lshl_add_u64 v[212:213], s[4:5], 0, v[198:199]
	s_mov_b32 m0, s42
	s_nop 0
	global_load_lds_dwordx4 v[212:213], off
	s_waitcnt vmcnt(8)
	s_waitcnt lgkmcnt(0)
	s_barrier
	s_setprio 1
	v_mfma_f32_16x16x32_bf16 v[126:129], v[130:133], v[162:165], v[126:129]
	v_mfma_f32_16x16x32_bf16 v[126:129], v[134:137], v[166:169], v[126:129]
	v_mfma_f32_16x16x32_bf16 v[122:125], v[142:145], v[166:169], v[122:125]
	v_mfma_f32_16x16x32_bf16 v[122:125], v[138:141], v[162:165], v[122:125]
	v_mfma_f32_16x16x32_bf16 v[106:109], v[138:141], v[170:173], v[106:109]
	v_mfma_f32_16x16x32_bf16 v[106:109], v[142:145], v[174:177], v[106:109]
	v_mfma_f32_16x16x32_bf16 v[110:113], v[134:137], v[174:177], v[110:113]
	v_mfma_f32_16x16x32_bf16 v[110:113], v[130:133], v[170:173], v[110:113]
	v_mfma_f32_16x16x32_bf16 v[94:97], v[130:133], v[178:181], v[94:97]
	v_mfma_f32_16x16x32_bf16 v[94:97], v[134:137], v[182:185], v[94:97]
	v_mfma_f32_16x16x32_bf16 v[90:93], v[142:145], v[182:185], v[90:93]
	v_mfma_f32_16x16x32_bf16 v[90:93], v[138:141], v[178:181], v[90:93]
	v_mfma_f32_16x16x32_bf16 v[74:77], v[138:141], v[186:189], v[74:77]
	v_mfma_f32_16x16x32_bf16 v[74:77], v[142:145], v[190:193], v[74:77]
	v_mfma_f32_16x16x32_bf16 v[78:81], v[134:137], v[190:193], v[78:81]
	v_mfma_f32_16x16x32_bf16 v[78:81], v[130:133], v[186:189], v[78:81]
	v_mfma_f32_16x16x32_bf16 v[118:121], v[146:149], v[162:165], v[118:121]
	v_mfma_f32_16x16x32_bf16 v[118:121], v[150:153], v[166:169], v[118:121]
	v_mfma_f32_16x16x32_bf16 v[114:117], v[158:161], v[166:169], v[114:117]
	v_mfma_f32_16x16x32_bf16 v[114:117], v[154:157], v[162:165], v[114:117]
	v_mfma_f32_16x16x32_bf16 v[98:101], v[154:157], v[170:173], v[98:101]
	v_mfma_f32_16x16x32_bf16 v[98:101], v[158:161], v[174:177], v[98:101]
	v_mfma_f32_16x16x32_bf16 v[102:105], v[150:153], v[174:177], v[102:105]
	v_mfma_f32_16x16x32_bf16 v[102:105], v[146:149], v[170:173], v[102:105]
	v_mfma_f32_16x16x32_bf16 v[86:89], v[146:149], v[178:181], v[86:89]
	v_mfma_f32_16x16x32_bf16 v[86:89], v[150:153], v[182:185], v[86:89]
	v_mfma_f32_16x16x32_bf16 v[82:85], v[158:161], v[182:185], v[82:85]
	v_mfma_f32_16x16x32_bf16 v[82:85], v[154:157], v[178:181], v[82:85]
	v_mfma_f32_16x16x32_bf16 v[66:69], v[154:157], v[186:189], v[66:69]
	v_mfma_f32_16x16x32_bf16 v[66:69], v[158:161], v[190:193], v[66:69]
	v_mfma_f32_16x16x32_bf16 v[70:73], v[150:153], v[190:193], v[70:73]
	v_mfma_f32_16x16x32_bf16 v[70:73], v[146:149], v[186:189], v[70:73]
	s_setprio 0
	s_barrier
	s_add_i32 s4, s52, s1
	v_lshl_add_u64 v[194:195], v[194:195], 0, s[34:35]
	s_mov_b32 m0, s4
	ds_read_b128 v[162:165], v243 offset:49152
	ds_read_b128 v[166:169], v243 offset:50176
	ds_read_b128 v[170:173], v243 offset:51200
	ds_read_b128 v[174:177], v243 offset:52224
	ds_read_b128 v[178:181], v243 offset:53248
	ds_read_b128 v[182:185], v243 offset:54272
	ds_read_b128 v[186:189], v243 offset:55296
	ds_read_b128 v[190:193], v243 offset:56320
	global_load_lds_dwordx4 v[194:195], off
	s_add_i32 m0, s4, 0x2000
	s_add_u32 s4, s30, 0x160080
	v_lshl_add_u64 v[194:195], v[206:207], 0, s[34:35]
	s_addc_u32 s5, s31, 0
	s_add_i32 s28, s53, s1
	global_load_lds_dwordx4 v[194:195], off
	v_lshl_add_u64 v[194:195], s[4:5], 0, v[32:33]
	s_mov_b32 m0, s28
	s_nop 0
	global_load_lds_dwordx4 v[194:195], off
	v_lshl_add_u64 v[194:195], s[4:5], 0, v[200:201]
	s_add_i32 m0, s28, 0x2000
	s_nop 0
	global_load_lds_dwordx4 v[194:195], off
	v_lshl_add_u64 v[194:195], v[208:209], 0, s[34:35]
	s_mov_b32 m0, s44
	s_nop 0
	global_load_lds_dwordx4 v[194:195], off
	v_lshl_add_u64 v[194:195], v[210:211], 0, s[34:35]
	s_mov_b32 m0, s45
	s_nop 0
	global_load_lds_dwordx4 v[194:195], off
	s_waitcnt vmcnt(8)
	s_waitcnt lgkmcnt(0)
	s_barrier
	s_setprio 1
	v_mfma_f32_16x16x32_bf16 v[62:65], v[130:133], v[162:165], v[62:65]
	v_mfma_f32_16x16x32_bf16 v[62:65], v[134:137], v[166:169], v[62:65]
	v_mfma_f32_16x16x32_bf16 v[58:61], v[142:145], v[166:169], v[58:61]
	v_mfma_f32_16x16x32_bf16 v[58:61], v[138:141], v[162:165], v[58:61]
	v_mfma_f32_16x16x32_bf16 v[42:45], v[138:141], v[170:173], v[42:45]
	v_mfma_f32_16x16x32_bf16 v[42:45], v[142:145], v[174:177], v[42:45]
	v_mfma_f32_16x16x32_bf16 v[46:49], v[134:137], v[174:177], v[46:49]
	v_mfma_f32_16x16x32_bf16 v[46:49], v[130:133], v[170:173], v[46:49]
	v_mfma_f32_16x16x32_bf16 v[28:31], v[130:133], v[178:181], v[28:31]
	v_mfma_f32_16x16x32_bf16 v[28:31], v[134:137], v[182:185], v[28:31]
	v_mfma_f32_16x16x32_bf16 v[24:27], v[142:145], v[182:185], v[24:27]
	v_mfma_f32_16x16x32_bf16 v[24:27], v[138:141], v[178:181], v[24:27]
	v_mfma_f32_16x16x32_bf16 v[8:11], v[138:141], v[186:189], v[8:11]
	v_mfma_f32_16x16x32_bf16 v[8:11], v[142:145], v[190:193], v[8:11]
	v_mfma_f32_16x16x32_bf16 v[12:15], v[134:137], v[190:193], v[12:15]
	v_mfma_f32_16x16x32_bf16 v[12:15], v[130:133], v[186:189], v[12:15]
	v_mfma_f32_16x16x32_bf16 v[54:57], v[146:149], v[162:165], v[54:57]
	v_mfma_f32_16x16x32_bf16 v[54:57], v[150:153], v[166:169], v[54:57]
	v_mfma_f32_16x16x32_bf16 v[50:53], v[158:161], v[166:169], v[50:53]
	v_mfma_f32_16x16x32_bf16 v[50:53], v[154:157], v[162:165], v[50:53]
	v_mfma_f32_16x16x32_bf16 v[34:37], v[154:157], v[170:173], v[34:37]
	v_mfma_f32_16x16x32_bf16 v[34:37], v[158:161], v[174:177], v[34:37]
	v_mfma_f32_16x16x32_bf16 v[38:41], v[150:153], v[174:177], v[38:41]
	v_mfma_f32_16x16x32_bf16 v[38:41], v[146:149], v[170:173], v[38:41]
	v_mfma_f32_16x16x32_bf16 v[20:23], v[146:149], v[178:181], v[20:23]
	v_mfma_f32_16x16x32_bf16 v[20:23], v[150:153], v[182:185], v[20:23]
	v_mfma_f32_16x16x32_bf16 v[16:19], v[158:161], v[182:185], v[16:19]
	v_mfma_f32_16x16x32_bf16 v[16:19], v[154:157], v[178:181], v[16:19]
	v_mfma_f32_16x16x32_bf16 v[0:3], v[154:157], v[186:189], v[0:3]
	v_mfma_f32_16x16x32_bf16 v[0:3], v[158:161], v[190:193], v[0:3]
	v_mfma_f32_16x16x32_bf16 v[4:7], v[150:153], v[190:193], v[4:7]
	v_mfma_f32_16x16x32_bf16 v[4:7], v[146:149], v[186:189], v[4:7]
	s_setprio 0
	s_barrier
	s_add_i32 s51, s51, 2
	s_add_u32 s33, s33, 0x100
	s_addc_u32 s50, s50, 0
	s_cmpk_gt_u32 s51, 0x55
	s_mov_b64 s[4:5], s[6:7]
	s_cbranch_scc0 .LBB0_755
	s_and_b64 vcc, exec, s[18:19]
	s_cbranch_vccz .LBB0_758
	s_barrier

.LBB0_888:
	s_add_u32 s38, s16, s30
	s_addc_u32 s39, s17, s31
	s_add_u32 s38, s38, 0x100
	s_addc_u32 s39, s39, 0
	s_add_u32 s54, s50, s30
	s_addc_u32 s55, s51, s31
	s_add_i32 s56, 0, 0x10000
	s_cmpk_eq_i32 s30, 0xf00
	s_cselect_b32 s41, s29, s39
	s_cselect_b32 s40, s28, s38
	s_cselect_b32 s39, s21, s55
	s_cselect_b32 s38, s52, s54
	s_add_i32 s57, 0, 0x14000
	v_add_u32_e32 v146, s56, v178
	v_add_u32_e32 v172, s57, v178
	ds_read_b128 v[134:137], v146
	ds_read_b128 v[138:141], v146 offset:1024
	ds_read_b128 v[142:145], v146 offset:2048
	ds_read_b128 v[146:149], v146 offset:3072
	ds_read_b128 v[150:153], v172
	ds_read_b128 v[154:157], v172 offset:1024
	ds_read_b128 v[158:161], v172 offset:2048
	ds_read_b128 v[172:175], v172 offset:3072
	v_lshl_add_u64 v[212:213], v[130:131], 0, s[30:31]
	s_add_i32 m0, s24, 0xc000
	ds_read_b128 v[180:183], v179
	ds_read_b128 v[184:187], v179 offset:1024
	ds_read_b128 v[188:191], v179 offset:2048
	ds_read_b128 v[192:195], v179 offset:3072
	ds_read_b128 v[196:199], v179 offset:4096
	ds_read_b128 v[200:203], v179 offset:5120
	ds_read_b128 v[204:207], v179 offset:6144
	ds_read_b128 v[208:211], v179 offset:7168
	global_load_lds_dwordx4 v[212:213], off
	v_lshl_add_u64 v[212:213], v[132:133], 0, s[30:31]
	s_add_i32 m0, s24, 0xe000
	s_nop 0
	global_load_lds_dwordx4 v[212:213], off
	s_waitcnt vmcnt(8)
	s_waitcnt lgkmcnt(0)
	s_barrier
	s_setprio 1
	v_mfma_f32_16x16x32_bf16 v[82:85], v[134:137], v[180:183], v[82:85]
	v_mfma_f32_16x16x32_bf16 v[82:85], v[138:141], v[184:187], v[82:85]
	v_mfma_f32_16x16x32_bf16 v[78:81], v[146:149], v[184:187], v[78:81]
	v_mfma_f32_16x16x32_bf16 v[78:81], v[142:145], v[180:183], v[78:81]
	v_mfma_f32_16x16x32_bf16 v[70:73], v[142:145], v[188:191], v[70:73]
	v_mfma_f32_16x16x32_bf16 v[70:73], v[146:149], v[192:195], v[70:73]
	v_mfma_f32_16x16x32_bf16 v[74:77], v[138:141], v[192:195], v[74:77]
	v_mfma_f32_16x16x32_bf16 v[74:77], v[134:137], v[188:191], v[74:77]
	v_mfma_f32_16x16x32_bf16 v[66:69], v[134:137], v[196:199], v[66:69]
	v_mfma_f32_16x16x32_bf16 v[66:69], v[138:141], v[200:203], v[66:69]
	v_mfma_f32_16x16x32_bf16 v[62:65], v[146:149], v[200:203], v[62:65]
	v_mfma_f32_16x16x32_bf16 v[62:65], v[142:145], v[196:199], v[62:65]
	v_mfma_f32_16x16x32_bf16 v[54:57], v[142:145], v[204:207], v[54:57]
	v_mfma_f32_16x16x32_bf16 v[54:57], v[146:149], v[208:211], v[54:57]
	v_mfma_f32_16x16x32_bf16 v[58:61], v[138:141], v[208:211], v[58:61]
	v_mfma_f32_16x16x32_bf16 v[58:61], v[134:137], v[204:207], v[58:61]
	v_mfma_f32_16x16x32_bf16 v[50:53], v[150:153], v[180:183], v[50:53]
	v_mfma_f32_16x16x32_bf16 v[50:53], v[154:157], v[184:187], v[50:53]
	v_mfma_f32_16x16x32_bf16 v[46:49], v[172:175], v[184:187], v[46:49]
	v_mfma_f32_16x16x32_bf16 v[46:49], v[158:161], v[180:183], v[46:49]
	v_mfma_f32_16x16x32_bf16 v[38:41], v[158:161], v[188:191], v[38:41]
	v_mfma_f32_16x16x32_bf16 v[38:41], v[172:175], v[192:195], v[38:41]
	v_mfma_f32_16x16x32_bf16 v[42:45], v[154:157], v[192:195], v[42:45]
	v_mfma_f32_16x16x32_bf16 v[42:45], v[150:153], v[188:191], v[42:45]
	v_mfma_f32_16x16x32_bf16 v[34:37], v[150:153], v[196:199], v[34:37]
	v_mfma_f32_16x16x32_bf16 v[34:37], v[154:157], v[200:203], v[34:37]
	v_mfma_f32_16x16x32_bf16 v[28:31], v[172:175], v[200:203], v[28:31]
	v_mfma_f32_16x16x32_bf16 v[28:31], v[158:161], v[196:199], v[28:31]
	v_mfma_f32_16x16x32_bf16 v[20:23], v[158:161], v[204:207], v[20:23]
	v_mfma_f32_16x16x32_bf16 v[20:23], v[172:175], v[208:211], v[20:23]
	v_mfma_f32_16x16x32_bf16 v[24:27], v[154:157], v[208:211], v[24:27]
	v_mfma_f32_16x16x32_bf16 v[24:27], v[150:153], v[204:207], v[24:27]
	s_setprio 0
	s_barrier
	s_add_i32 s54, s56, s13
	v_lshl_add_u64 v[212:213], s[38:39], 0, v[32:33]
	s_mov_b32 m0, s54
	ds_read_b128 v[180:183], v179 offset:16384
	ds_read_b128 v[184:187], v179 offset:17408
	ds_read_b128 v[188:191], v179 offset:18432
	ds_read_b128 v[192:195], v179 offset:19456
	ds_read_b128 v[196:199], v179 offset:20480
	ds_read_b128 v[200:203], v179 offset:21504
	ds_read_b128 v[204:207], v179 offset:22528
	ds_read_b128 v[208:211], v179 offset:23552
	global_load_lds_dwordx4 v[212:213], off
	s_add_i32 m0, s54, 0x2000
	s_add_u32 s54, s38, 0x80000
	v_lshl_add_u64 v[214:215], s[38:39], 0, v[166:167]
	s_addc_u32 s55, s39, 0
	s_add_i32 s56, s57, s13
	global_load_lds_dwordx4 v[214:215], off
	v_lshl_add_u64 v[216:217], s[54:55], 0, v[32:33]
	s_mov_b32 m0, s56
	v_lshl_add_u64 v[220:221], s[40:41], 0, v[164:165]
	global_load_lds_dwordx4 v[216:217], off
	v_lshl_add_u64 v[216:217], s[54:55], 0, v[166:167]
	s_add_i32 m0, s56, 0x2000
	s_nop 0
	global_load_lds_dwordx4 v[216:217], off
	v_lshl_add_u64 v[216:217], s[40:41], 0, v[162:163]
	s_mov_b32 m0, s24
	s_nop 0
	global_load_lds_dwordx4 v[216:217], off
	s_mov_b32 m0, s25
	s_nop 0
	global_load_lds_dwordx4 v[220:221], off
	s_waitcnt vmcnt(8)
	s_waitcnt lgkmcnt(0)
	s_barrier
	s_setprio 1
	v_mfma_f32_16x16x32_bf16 v[16:19], v[134:137], v[180:183], v[16:19]
	v_mfma_f32_16x16x32_bf16 v[16:19], v[138:141], v[184:187], v[16:19]
	v_mfma_f32_16x16x32_bf16 v[12:15], v[146:149], v[184:187], v[12:15]
	v_mfma_f32_16x16x32_bf16 v[12:15], v[142:145], v[180:183], v[12:15]
	v_mfma_f32_16x16x32_bf16 v[4:7], v[142:145], v[188:191], v[4:7]
	v_mfma_f32_16x16x32_bf16 v[4:7], v[146:149], v[192:195], v[4:7]
	v_mfma_f32_16x16x32_bf16 v[8:11], v[138:141], v[192:195], v[8:11]
	v_mfma_f32_16x16x32_bf16 v[8:11], v[134:137], v[188:191], v[8:11]
	v_mfma_f32_16x16x32_bf16 v[0:3], v[134:137], v[196:199], v[0:3]
	v_mfma_f32_16x16x32_bf16 v[0:3], v[138:141], v[200:203], v[0:3]
	v_mfma_f32_16x16x32_bf16 v[86:89], v[146:149], v[200:203], v[86:89]
	v_mfma_f32_16x16x32_bf16 v[86:89], v[142:145], v[196:199], v[86:89]
	v_mfma_f32_16x16x32_bf16 v[94:97], v[142:145], v[204:207], v[94:97]
	v_mfma_f32_16x16x32_bf16 v[94:97], v[146:149], v[208:211], v[94:97]
	v_mfma_f32_16x16x32_bf16 v[90:93], v[138:141], v[208:211], v[90:93]
	v_mfma_f32_16x16x32_bf16 v[90:93], v[134:137], v[204:207], v[90:93]
	v_mfma_f32_16x16x32_bf16 v[98:101], v[150:153], v[180:183], v[98:101]
	v_mfma_f32_16x16x32_bf16 v[98:101], v[154:157], v[184:187], v[98:101]
	v_mfma_f32_16x16x32_bf16 v[102:105], v[172:175], v[184:187], v[102:105]
	v_mfma_f32_16x16x32_bf16 v[102:105], v[158:161], v[180:183], v[102:105]
	v_mfma_f32_16x16x32_bf16 v[110:113], v[158:161], v[188:191], v[110:113]
	v_mfma_f32_16x16x32_bf16 v[110:113], v[172:175], v[192:195], v[110:113]
	v_mfma_f32_16x16x32_bf16 v[106:109], v[154:157], v[192:195], v[106:109]
	v_mfma_f32_16x16x32_bf16 v[106:109], v[150:153], v[188:191], v[106:109]
	v_mfma_f32_16x16x32_bf16 v[114:117], v[150:153], v[196:199], v[114:117]
	v_mfma_f32_16x16x32_bf16 v[114:117], v[154:157], v[200:203], v[114:117]
	v_mfma_f32_16x16x32_bf16 v[118:121], v[172:175], v[200:203], v[118:121]
	v_mfma_f32_16x16x32_bf16 v[118:121], v[158:161], v[196:199], v[118:121]
	v_mfma_f32_16x16x32_bf16 v[126:129], v[158:161], v[204:207], v[126:129]
	v_mfma_f32_16x16x32_bf16 v[126:129], v[172:175], v[208:211], v[126:129]
	v_mfma_f32_16x16x32_bf16 v[122:125], v[154:157], v[208:211], v[122:125]
	v_mfma_f32_16x16x32_bf16 v[122:125], v[150:153], v[204:207], v[122:125]
	s_setprio 0
	s_barrier
	s_add_i32 s54, 0, 0x18000
	s_add_i32 s55, 0, 0x1c000
	v_add_u32_e32 v146, s54, v178
	v_add_u32_e32 v172, s55, v178
	ds_read_b128 v[134:137], v146
	ds_read_b128 v[138:141], v146 offset:1024
	ds_read_b128 v[142:145], v146 offset:2048
	ds_read_b128 v[146:149], v146 offset:3072
	ds_read_b128 v[150:153], v172
	ds_read_b128 v[154:157], v172 offset:1024
	ds_read_b128 v[158:161], v172 offset:2048
	ds_read_b128 v[172:175], v172 offset:3072
	s_add_u32 s40, s40, 0x80000
	s_addc_u32 s41, s41, 0
	s_mov_b32 m0, s33
	v_lshl_add_u64 v[222:223], s[40:41], 0, v[162:163]
	ds_read_b128 v[180:183], v179 offset:32768
	ds_read_b128 v[184:187], v179 offset:33792
	ds_read_b128 v[188:191], v179 offset:34816
	ds_read_b128 v[192:195], v179 offset:35840
	ds_read_b128 v[196:199], v179 offset:36864
	ds_read_b128 v[200:203], v179 offset:37888
	ds_read_b128 v[204:207], v179 offset:38912
	ds_read_b128 v[208:211], v179 offset:39936
	global_load_lds_dwordx4 v[222:223], off
	v_lshl_add_u64 v[222:223], s[40:41], 0, v[164:165]
	s_mov_b32 m0, s36
	s_nop 0
	global_load_lds_dwordx4 v[222:223], off
	s_waitcnt vmcnt(8)
	s_waitcnt lgkmcnt(0)
	s_barrier
	s_setprio 1
	v_mfma_f32_16x16x32_bf16 v[82:85], v[134:137], v[180:183], v[82:85]
	v_mfma_f32_16x16x32_bf16 v[82:85], v[138:141], v[184:187], v[82:85]
	v_mfma_f32_16x16x32_bf16 v[78:81], v[146:149], v[184:187], v[78:81]
	v_mfma_f32_16x16x32_bf16 v[78:81], v[142:145], v[180:183], v[78:81]
	v_mfma_f32_16x16x32_bf16 v[70:73], v[142:145], v[188:191], v[70:73]
	v_mfma_f32_16x16x32_bf16 v[70:73], v[146:149], v[192:195], v[70:73]
	v_mfma_f32_16x16x32_bf16 v[74:77], v[138:141], v[192:195], v[74:77]
	v_mfma_f32_16x16x32_bf16 v[74:77], v[134:137], v[188:191], v[74:77]
	v_mfma_f32_16x16x32_bf16 v[66:69], v[134:137], v[196:199], v[66:69]
	v_mfma_f32_16x16x32_bf16 v[66:69], v[138:141], v[200:203], v[66:69]
	v_mfma_f32_16x16x32_bf16 v[62:65], v[146:149], v[200:203], v[62:65]
	v_mfma_f32_16x16x32_bf16 v[62:65], v[142:145], v[196:199], v[62:65]
	v_mfma_f32_16x16x32_bf16 v[54:57], v[142:145], v[204:207], v[54:57]
	v_mfma_f32_16x16x32_bf16 v[54:57], v[146:149], v[208:211], v[54:57]
	v_mfma_f32_16x16x32_bf16 v[58:61], v[138:141], v[208:211], v[58:61]
	v_mfma_f32_16x16x32_bf16 v[58:61], v[134:137], v[204:207], v[58:61]
	v_mfma_f32_16x16x32_bf16 v[50:53], v[150:153], v[180:183], v[50:53]
	v_mfma_f32_16x16x32_bf16 v[50:53], v[154:157], v[184:187], v[50:53]
	v_mfma_f32_16x16x32_bf16 v[46:49], v[172:175], v[184:187], v[46:49]
	v_mfma_f32_16x16x32_bf16 v[46:49], v[158:161], v[180:183], v[46:49]
	v_mfma_f32_16x16x32_bf16 v[38:41], v[158:161], v[188:191], v[38:41]
	v_mfma_f32_16x16x32_bf16 v[38:41], v[172:175], v[192:195], v[38:41]
	v_mfma_f32_16x16x32_bf16 v[42:45], v[154:157], v[192:195], v[42:45]
	v_mfma_f32_16x16x32_bf16 v[42:45], v[150:153], v[188:191], v[42:45]
	v_mfma_f32_16x16x32_bf16 v[34:37], v[150:153], v[196:199], v[34:37]
	v_mfma_f32_16x16x32_bf16 v[34:37], v[154:157], v[200:203], v[34:37]
	v_mfma_f32_16x16x32_bf16 v[28:31], v[172:175], v[200:203], v[28:31]
	v_mfma_f32_16x16x32_bf16 v[28:31], v[158:161], v[196:199], v[28:31]
	v_mfma_f32_16x16x32_bf16 v[20:23], v[158:161], v[204:207], v[20:23]
	v_mfma_f32_16x16x32_bf16 v[20:23], v[172:175], v[208:211], v[20:23]
	v_mfma_f32_16x16x32_bf16 v[24:27], v[154:157], v[208:211], v[24:27]
	v_mfma_f32_16x16x32_bf16 v[24:27], v[150:153], v[204:207], v[24:27]
	s_setprio 0
	s_barrier
	s_add_i32 s40, s54, s13
	v_lshl_add_u64 v[212:213], v[212:213], 0, s[34:35]
	s_mov_b32 m0, s40
	ds_read_b128 v[180:183], v179 offset:49152
	ds_read_b128 v[184:187], v179 offset:50176
	ds_read_b128 v[188:191], v179 offset:51200
	ds_read_b128 v[192:195], v179 offset:52224
	ds_read_b128 v[196:199], v179 offset:53248
	ds_read_b128 v[200:203], v179 offset:54272
	ds_read_b128 v[204:207], v179 offset:55296
	ds_read_b128 v[208:211], v179 offset:56320
	global_load_lds_dwordx4 v[212:213], off
	s_add_i32 m0, s40, 0x2000
	s_add_u32 s38, s38, 0x80080
	v_lshl_add_u64 v[212:213], v[214:215], 0, s[34:35]
	s_addc_u32 s39, s39, 0
	s_add_i32 s40, s55, s13
	global_load_lds_dwordx4 v[212:213], off
	v_lshl_add_u64 v[212:213], s[38:39], 0, v[32:33]
	s_mov_b32 m0, s40
	s_nop 0
	global_load_lds_dwordx4 v[212:213], off
	v_lshl_add_u64 v[212:213], s[38:39], 0, v[166:167]
	s_add_i32 m0, s40, 0x2000
	s_nop 0
	global_load_lds_dwordx4 v[212:213], off
	v_lshl_add_u64 v[212:213], v[216:217], 0, s[34:35]
	s_mov_b32 m0, s43
	s_nop 0
	global_load_lds_dwordx4 v[212:213], off
	v_lshl_add_u64 v[212:213], v[220:221], 0, s[34:35]
	s_mov_b32 m0, s44
	s_nop 0
	global_load_lds_dwordx4 v[212:213], off
	s_waitcnt vmcnt(8)
	s_waitcnt lgkmcnt(0)
	s_barrier
	s_setprio 1
	v_mfma_f32_16x16x32_bf16 v[16:19], v[134:137], v[180:183], v[16:19]
	v_mfma_f32_16x16x32_bf16 v[16:19], v[138:141], v[184:187], v[16:19]
	v_mfma_f32_16x16x32_bf16 v[12:15], v[146:149], v[184:187], v[12:15]
	v_mfma_f32_16x16x32_bf16 v[12:15], v[142:145], v[180:183], v[12:15]
	v_mfma_f32_16x16x32_bf16 v[4:7], v[142:145], v[188:191], v[4:7]
	v_mfma_f32_16x16x32_bf16 v[4:7], v[146:149], v[192:195], v[4:7]
	v_mfma_f32_16x16x32_bf16 v[8:11], v[138:141], v[192:195], v[8:11]
	v_mfma_f32_16x16x32_bf16 v[8:11], v[134:137], v[188:191], v[8:11]
	v_mfma_f32_16x16x32_bf16 v[0:3], v[134:137], v[196:199], v[0:3]
	v_mfma_f32_16x16x32_bf16 v[0:3], v[138:141], v[200:203], v[0:3]
	v_mfma_f32_16x16x32_bf16 v[86:89], v[146:149], v[200:203], v[86:89]
	v_mfma_f32_16x16x32_bf16 v[86:89], v[142:145], v[196:199], v[86:89]
	v_mfma_f32_16x16x32_bf16 v[94:97], v[142:145], v[204:207], v[94:97]
	v_mfma_f32_16x16x32_bf16 v[94:97], v[146:149], v[208:211], v[94:97]
	v_mfma_f32_16x16x32_bf16 v[90:93], v[138:141], v[208:211], v[90:93]
	v_mfma_f32_16x16x32_bf16 v[90:93], v[134:137], v[204:207], v[90:93]
	v_mfma_f32_16x16x32_bf16 v[98:101], v[150:153], v[180:183], v[98:101]
	v_mfma_f32_16x16x32_bf16 v[98:101], v[154:157], v[184:187], v[98:101]
	v_mfma_f32_16x16x32_bf16 v[102:105], v[172:175], v[184:187], v[102:105]
	v_mfma_f32_16x16x32_bf16 v[102:105], v[158:161], v[180:183], v[102:105]
	v_mfma_f32_16x16x32_bf16 v[110:113], v[158:161], v[188:191], v[110:113]
	v_mfma_f32_16x16x32_bf16 v[110:113], v[172:175], v[192:195], v[110:113]
	v_mfma_f32_16x16x32_bf16 v[106:109], v[154:157], v[192:195], v[106:109]
	v_mfma_f32_16x16x32_bf16 v[106:109], v[150:153], v[188:191], v[106:109]
	v_mfma_f32_16x16x32_bf16 v[114:117], v[150:153], v[196:199], v[114:117]
	v_mfma_f32_16x16x32_bf16 v[114:117], v[154:157], v[200:203], v[114:117]
	v_mfma_f32_16x16x32_bf16 v[118:121], v[172:175], v[200:203], v[118:121]
	v_mfma_f32_16x16x32_bf16 v[118:121], v[158:161], v[196:199], v[118:121]
	v_mfma_f32_16x16x32_bf16 v[126:129], v[158:161], v[204:207], v[126:129]
	v_mfma_f32_16x16x32_bf16 v[126:129], v[172:175], v[208:211], v[126:129]
	v_mfma_f32_16x16x32_bf16 v[122:125], v[154:157], v[208:211], v[122:125]
	v_mfma_f32_16x16x32_bf16 v[122:125], v[150:153], v[204:207], v[122:125]
	s_setprio 0
	s_barrier
	s_add_i32 s53, s53, 2
	s_add_u32 s30, s30, 0x100
	s_addc_u32 s31, s31, 0
	s_cmp_gt_u32 s53, 29
	s_cbranch_scc0 .LBB0_888
	s_and_b64 vcc, exec, s[18:19]
	s_cbranch_vccz .LBB0_891
	s_barrier
